# chain-produced data (out-proj result, ssq, xb, rn) is read with L1-bypassing sc1 loads in D2 and A, so the two 4-workgroup chain syncs need no L1 invalidate on a one-XCC group (invalidate kept otherwi
# speedup vs baseline: 1.0775x; 1.0094x over previous
; DI char* opq(char* q) { size_t z = 0; asm volatile("" : "+s"(z)); return q + z; }
; DI int tidx() { int t = threadIdx.x; asm volatile("" : "+v"(t)); return t; }
; #define GLOAD(dst, kt_) _Pragma("unroll") for (int i = 0; i < NCH; ++i) { dst[i] = (i < NCHW) ? ldw(i, tid >> 3, (kt_) * 64 + (tid & 7) * 8) : ldx(i - NCHW, tid >> 3, (kt_) * 64 + (tid & 7) * 8); }
; #define LSTORE(src, base) _Pragma("unroll") for (int i = 0; i < NCH; ++i) { const int c = tid + 256 * i; *(u32x4*)((base) + (c >> 3) * 144 + (c & 7) * 16) = src[i]; }
; template <int WGN, int INS, int IMS, bool DB, class LdW, class LdX>
; DI void gemm_core(f32x16 (&acc)[INS][IMS], const int KT, LdW ldw, LdX ldx, char* lds, const int tid) {
;   constexpr int WGM = 4 / WGN;
;   constexpr int WROWS = WGN * 32 * INS, XROWS = WGM * 32 * IMS, NROWS = WROWS + XROWS, NCH = NROWS / 32, NCHW = WROWS / 32, BUFB = NROWS * 144;
;   const int lane = tid & 63, wid = tid >> 6, l31 = lane & 31, hi = lane >> 5;
;   const int wn = (WGN == 2) ? (wid >> 1) : wid, wm = (WGN == 2) ? (wid & 1) : 0;
;   const int offa = (wn * 32 * INS + l31) * 144 + hi * 16;
;   const int offb = (WROWS + wm * 32 * IMS + l31) * 144 + hi * 16;
; #pragma unroll
;   for (int a = 0; a < INS; ++a)
; #pragma unroll
;     for (int b = 0; b < IMS; ++b)
; #pragma unroll
;       for (int r = 0; r < 16; ++r) acc[a][b][r] = 0.f;
;     ...
;   if (DB) {
;     u32x4 preA[NCH], preB[NCH];
;     GLOAD(preA, 0)
;     GLOAD(preB, 1)
;     __syncthreads();
;     LSTORE(preA, lds)
;     __syncthreads();
; template <int NTW>
; DI void inproj_tile(const Params& p, int l, int mt, int ntile, char* lds) {
;   char* const ws_ = opq(p.ws);
;   const u16* W = (const u16*)(ws_ + OFF_WIN) + ((size_t)l * NP + ntile * 64 * NTW) * 1024;
;   const u16* X = (const u16*)(ws_ + OFF_XB) + (size_t)mt * 128 * 1024;
;   f32x16 acc[NTW][2];
;   const int tid = tidx();
;   gemm_core<2, NTW, 2, (NTW == 2)>(acc, 16, [&](int i, int r0, int k) -> u32x4 { return *(const u32x4*)((W + i * 32768) + (unsigned)(r0 * 1024 + k)); },
;                [&](int i, int r0, int k) -> u32x4 { return *(const u32x4*)((X + i * 32768) + (unsigned)(r0 * 1024 + k)); }, lds, tid);
.LBB0_163:
	s_lshl_b32 s0, s26, 4
	s_and_b32 s0, s0, 0x70
	s_bfe_u32 s1, s26, 0x40003
	s_or_b32 s4, s0, s1
	s_mov_b64 s[0:1], 0
	s_add_u32 s27, s90, s0
	s_addc_u32 s28, s91, s1
	s_lshl_b32 s0, s26, 1
	s_and_b32 s0, s0, 0xffffff00
	v_readlane_b32 s2, v234, 24
	s_ashr_i32 s1, s0, 31
	s_mulk_i32 s2, 0xd00
	s_add_u32 s2, s0, s2
	s_addc_u32 s3, s1, 0
	s_lshl_b64 s[2:3], s[2:3], 11
	s_add_u32 s2, s27, s2
	s_addc_u32 s3, s28, s3
	s_lshl_b32 s80, s4, 7
	s_lshl_b32 s4, s4, 18
	s_add_u32 s24, s27, s4
	s_addc_u32 s25, s28, 0
	s_add_u32 s4, s24, 0x2a40000
	s_addc_u32 s5, s25, 0
	v_mov_b32_e32 v181, v176
	v_and_b32_e32 v183, 0x5f, v181
	v_lshrrev_b32_e32 v185, 3, v181
	v_or_b32_e32 v254, s80, v183
	v_lshlrev_b32_e32 v254, 2, v254
	s_add_u32 s14, s27, 0x4a40000
	s_addc_u32 s15, s28, 0
	global_load_dword v252, v254, s[14:15] sc1
	global_load_dword v253, v254, s[14:15] offset:128 sc1
	v_and_b32_e32 v220, 63, v181
	v_lshrrev_b32_e32 v221, 6, v181
	v_lshrrev_b32_e32 v222, 3, v220
	v_readfirstlane_b32 s13, v221
	v_and_b32_e32 v223, 7, v220
	v_bfe_u32 v224, v220, 4, 2
	v_xor_b32_e32 v223, v223, v224
	v_lshlrev_b32_e32 v223, 4, v223
	v_and_b32_e32 v224, 1, v221
	v_lshrrev_b32_e32 v225, 1, v221
	v_lshlrev_b32_e32 v224, 5, v224
	v_lshl_add_u32 v224, v225, 7, v224
	v_add_u32_e32 v224, v224, v222
	v_lshl_add_u32 v225, v221, 5, v222
	v_lshl_or_b32 v210, v224, 11, v223
	v_lshl_or_b32 v216, v225, 11, v223
	v_xor_b32_e32 v224, 64, v210
	v_xor_b32_e32 v225, 64, v216
	v_add_u32_e32 v211, 0x3c00, v224
	v_add_u32_e32 v217, 0x3c00, v225
	v_add_u32_e32 v212, 0x7800, v210
	v_add_u32_e32 v218, 0x7800, v216
	v_add_u32_e32 v213, 0xb400, v224
	v_add_u32_e32 v219, 0xb400, v225
	v_and_b32_e32 v222, 31, v220
	v_lshrrev_b32_e32 v223, 5, v220
	v_bfe_u32 v224, v220, 1, 3
	v_xor_b32_e32 v223, v223, v224
	v_lshlrev_b32_e32 v223, 4, v223
	v_lshrrev_b32_e32 v224, 1, v221
	v_and_b32_e32 v225, 1, v221
	v_lshl_add_u32 v224, v224, 6, v222
	v_lshl_add_u32 v225, v225, 6, v222
	v_lshl_or_b32 v202, v224, 7, v223
	v_lshl_or_b32 v206, v225, 7, v223
	v_xor_b32_e32 v203, 32, v202
	v_xor_b32_e32 v207, 32, v206
	v_xor_b32_e32 v204, 64, v202
	v_xor_b32_e32 v208, 64, v206
	v_xor_b32_e32 v205, 96, v202
	v_xor_b32_e32 v209, 96, v206
	s_lshl_b32 s13, s13, 12
	s_sub_u32 s10, s4, 0x80
	s_subb_u32 s11, s5, 0
	s_add_u32 s8, s2, 0x1ff80
	s_addc_u32 s9, s3, 0
	s_sub_u32 s6, s2, 0x80
	s_subb_u32 s7, s3, 0
	s_mov_b32 s12, 0
	v_mov_b32_e32 v112, 0
	v_mov_b32_e32 v113, 0
	v_mov_b32_e32 v114, 0
	v_mov_b32_e32 v115, 0
	v_mov_b32_e32 v116, 0
	v_mov_b32_e32 v117, 0
	v_mov_b32_e32 v118, 0
	v_mov_b32_e32 v119, 0
	v_mov_b32_e32 v120, 0
	v_mov_b32_e32 v121, 0
	v_mov_b32_e32 v122, 0
	v_mov_b32_e32 v123, 0
	v_mov_b32_e32 v124, 0
	v_mov_b32_e32 v125, 0
	v_mov_b32_e32 v126, 0
	v_mov_b32_e32 v127, 0
	v_mov_b32_e32 v48, 0
	v_mov_b32_e32 v49, 0
	v_mov_b32_e32 v50, 0
	v_mov_b32_e32 v51, 0
	v_mov_b32_e32 v52, 0
	v_mov_b32_e32 v53, 0
	v_mov_b32_e32 v54, 0
	v_mov_b32_e32 v55, 0
	v_mov_b32_e32 v56, 0
	v_mov_b32_e32 v57, 0
	v_mov_b32_e32 v58, 0
	v_mov_b32_e32 v59, 0
	v_mov_b32_e32 v60, 0
	v_mov_b32_e32 v61, 0
	v_mov_b32_e32 v62, 0
	v_mov_b32_e32 v63, 0
	v_mov_b32_e32 v96, 0
	v_mov_b32_e32 v97, 0
	v_mov_b32_e32 v98, 0
	v_mov_b32_e32 v99, 0
	v_mov_b32_e32 v100, 0
	v_mov_b32_e32 v101, 0
	v_mov_b32_e32 v102, 0
	v_mov_b32_e32 v103, 0
	v_mov_b32_e32 v104, 0
	v_mov_b32_e32 v105, 0
	v_mov_b32_e32 v106, 0
	v_mov_b32_e32 v107, 0
	v_mov_b32_e32 v108, 0
	v_mov_b32_e32 v109, 0
	v_mov_b32_e32 v110, 0
	v_mov_b32_e32 v111, 0
	v_mov_b32_e32 v32, 0
	v_mov_b32_e32 v33, 0
	v_mov_b32_e32 v34, 0
	v_mov_b32_e32 v35, 0
	v_mov_b32_e32 v36, 0
	v_mov_b32_e32 v37, 0
	v_mov_b32_e32 v38, 0
	v_mov_b32_e32 v39, 0
	v_mov_b32_e32 v40, 0
	v_mov_b32_e32 v41, 0
	v_mov_b32_e32 v42, 0
	v_mov_b32_e32 v43, 0
	v_mov_b32_e32 v44, 0
	v_mov_b32_e32 v45, 0
	v_mov_b32_e32 v46, 0
	v_mov_b32_e32 v47, 0
	v_mov_b32_e32 v80, 0
	v_mov_b32_e32 v81, 0
	v_mov_b32_e32 v82, 0
	v_mov_b32_e32 v83, 0
	v_mov_b32_e32 v84, 0
	v_mov_b32_e32 v85, 0
	v_mov_b32_e32 v86, 0
	v_mov_b32_e32 v87, 0
	v_mov_b32_e32 v88, 0
	v_mov_b32_e32 v89, 0
	v_mov_b32_e32 v90, 0
	v_mov_b32_e32 v91, 0
	v_mov_b32_e32 v92, 0
	v_mov_b32_e32 v93, 0
	v_mov_b32_e32 v94, 0
	v_mov_b32_e32 v95, 0
	v_mov_b32_e32 v16, 0
	v_mov_b32_e32 v17, 0
	v_mov_b32_e32 v18, 0
	v_mov_b32_e32 v19, 0
	v_mov_b32_e32 v20, 0
	v_mov_b32_e32 v21, 0
	v_mov_b32_e32 v22, 0
	v_mov_b32_e32 v23, 0
	v_mov_b32_e32 v24, 0
	v_mov_b32_e32 v25, 0
	v_mov_b32_e32 v26, 0
	v_mov_b32_e32 v27, 0
	v_mov_b32_e32 v28, 0
	v_mov_b32_e32 v29, 0
	v_mov_b32_e32 v30, 0
	v_mov_b32_e32 v31, 0
	v_mov_b32_e32 v64, 0
	v_mov_b32_e32 v65, 0
	v_mov_b32_e32 v66, 0
	v_mov_b32_e32 v67, 0
	v_mov_b32_e32 v68, 0
	v_mov_b32_e32 v69, 0
	v_mov_b32_e32 v70, 0
	v_mov_b32_e32 v71, 0
	v_mov_b32_e32 v72, 0
	v_mov_b32_e32 v73, 0
	v_mov_b32_e32 v74, 0
	v_mov_b32_e32 v75, 0
	v_mov_b32_e32 v76, 0
	v_mov_b32_e32 v77, 0
	v_mov_b32_e32 v78, 0
	v_mov_b32_e32 v79, 0
	v_mov_b32_e32 v0, 0
	v_mov_b32_e32 v1, 0
	v_mov_b32_e32 v2, 0
	v_mov_b32_e32 v3, 0
	v_mov_b32_e32 v4, 0
	v_mov_b32_e32 v5, 0
	v_mov_b32_e32 v6, 0
	v_mov_b32_e32 v7, 0
	v_mov_b32_e32 v8, 0
	v_mov_b32_e32 v9, 0
	v_mov_b32_e32 v10, 0
	v_mov_b32_e32 v11, 0
	v_mov_b32_e32 v12, 0
	v_mov_b32_e32 v13, 0
	v_mov_b32_e32 v14, 0
	v_mov_b32_e32 v15, 0
	s_waitcnt lgkmcnt(0)
	s_barrier
	s_add_u32 s10, s10, 0x80
	s_addc_u32 s11, s11, 0
	s_add_u32 m0, s13, 0
	s_nop 0
	global_load_lds_dwordx4 v216, s[10:11] sc1
	global_load_lds_dwordx4 v217, s[10:11] offset:1024 sc1
	global_load_lds_dwordx4 v218, s[10:11] offset:2048 sc1
	global_load_lds_dwordx4 v219, s[10:11] offset:3072 sc1
	s_add_u32 s6, s6, 0x80
	s_addc_u32 s7, s7, 0
	s_add_u32 m0, s13, 32768
	s_nop 0
	global_load_lds_dwordx4 v210, s[6:7]
	global_load_lds_dwordx4 v211, s[6:7] offset:1024
	global_load_lds_dwordx4 v212, s[6:7] offset:2048
	global_load_lds_dwordx4 v213, s[6:7] offset:3072
; #define GLOAD(dst, kt_) _Pragma("unroll") for (int i = 0; i < NCH; ++i) { dst[i] = (i < NCHW) ? ldw(i, tid >> 3, (kt_) * 64 + (tid & 7) * 8) : ldx(i - NCHW, tid >> 3, (kt_) * 64 + (tid & 7) * 8); }
; #define LSTORE(src, base) _Pragma("unroll") for (int i = 0; i < NCH; ++i) { const int c = tid + 256 * i; *(u32x4*)((base) + (c >> 3) * 144 + (c & 7) * 16) = src[i]; }
; template <int WGN, int INS, int IMS, bool DB, class LdW, class LdX>
; DI void gemm_core(f32x16 (&acc)[INS][IMS], const int KT, LdW ldw, LdX ldx, char* lds, const int tid) {
;     ...
;     for (int kt = 0; kt < KT; kt += 2) {
;       if (kt + 2 < KT) { GLOAD(preA, kt + 2) }
;       COMPUTE_PIPE(lds)
;       LSTORE(preB, lds + BUFB)
;       __syncthreads();
;       if (kt + 3 < KT) { GLOAD(preB, kt + 3) }
;       COMPUTE_PIPE(lds + BUFB)
;       if (kt + 2 < KT) { LSTORE(preA, lds) }
;       __syncthreads();
;     }
; template <int NTW>
; DI void inproj_tile(const Params& p, int l, int mt, int ntile, char* lds) {
;     ...
;   gemm_core<2, NTW, 2, (NTW == 2)>(acc, 16, [&](int i, int r0, int k) -> u32x4 { return *(const u32x4*)((W + i * 32768) + (unsigned)(r0 * 1024 + k)); },
;                [&](int i, int r0, int k) -> u32x4 { return *(const u32x4*)((X + i * 32768) + (unsigned)(r0 * 1024 + k)); }, lds, tid);
.Lga_loop:
	s_waitcnt vmcnt(0)
	s_barrier
	ds_read_b128 v[160:163], v206 offset:0
	ds_read_b128 v[236:239], v206 offset:4096
	ds_read_b128 v[128:131], v202 offset:32768
	ds_read_b128 v[144:147], v202 offset:36864
	ds_read_b128 v[164:167], v207 offset:0
	ds_read_b128 v[240:243], v207 offset:4096
	ds_read_b128 v[132:135], v203 offset:32768
	ds_read_b128 v[148:151], v203 offset:36864
	s_add_u32 s8, s8, 0x80
	s_addc_u32 s9, s9, 0
	s_add_u32 m0, s13, 49152
	s_nop 0
	global_load_lds_dwordx4 v210, s[8:9]
	global_load_lds_dwordx4 v211, s[8:9] offset:1024
	global_load_lds_dwordx4 v212, s[8:9] offset:2048
	global_load_lds_dwordx4 v213, s[8:9] offset:3072
	s_add_u32 s10, s10, 0x80
	s_addc_u32 s11, s11, 0
	s_add_u32 m0, s13, 16384
	s_nop 0
	global_load_lds_dwordx4 v216, s[10:11] sc1
	global_load_lds_dwordx4 v217, s[10:11] offset:1024 sc1
	global_load_lds_dwordx4 v218, s[10:11] offset:2048 sc1
	global_load_lds_dwordx4 v219, s[10:11] offset:3072 sc1
	s_waitcnt lgkmcnt(4)
	v_mfma_f32_32x32x16_bf16 v[112:127], v[128:131], v[160:163], v[112:127]
	v_mfma_f32_32x32x16_bf16 v[48:63], v[128:131], v[236:239], v[48:63]
	ds_read_b128 v[168:171], v208 offset:0
	ds_read_b128 v[244:247], v208 offset:4096
	ds_read_b128 v[136:139], v204 offset:32768
	ds_read_b128 v[152:155], v204 offset:36864
	v_mfma_f32_32x32x16_bf16 v[96:111], v[144:147], v[160:163], v[96:111]
	v_mfma_f32_32x32x16_bf16 v[32:47], v[144:147], v[236:239], v[32:47]
	s_waitcnt lgkmcnt(4)
	v_mfma_f32_32x32x16_bf16 v[112:127], v[132:135], v[164:167], v[112:127]
	v_mfma_f32_32x32x16_bf16 v[48:63], v[132:135], v[240:243], v[48:63]
	ds_read_b128 v[172:175], v209 offset:0
	ds_read_b128 v[248:251], v209 offset:4096
	ds_read_b128 v[140:143], v205 offset:32768
	ds_read_b128 v[156:159], v205 offset:36864
	v_mfma_f32_32x32x16_bf16 v[96:111], v[148:151], v[164:167], v[96:111]
	v_mfma_f32_32x32x16_bf16 v[32:47], v[148:151], v[240:243], v[32:47]
	s_waitcnt lgkmcnt(4)
	v_mfma_f32_32x32x16_bf16 v[112:127], v[136:139], v[168:171], v[112:127]
	v_mfma_f32_32x32x16_bf16 v[48:63], v[136:139], v[244:247], v[48:63]
	v_mfma_f32_32x32x16_bf16 v[96:111], v[152:155], v[168:171], v[96:111]
	v_mfma_f32_32x32x16_bf16 v[32:47], v[152:155], v[244:247], v[32:47]
	s_waitcnt lgkmcnt(0)
	v_mfma_f32_32x32x16_bf16 v[112:127], v[140:143], v[172:175], v[112:127]
	v_mfma_f32_32x32x16_bf16 v[48:63], v[140:143], v[248:251], v[48:63]
	v_mfma_f32_32x32x16_bf16 v[96:111], v[156:159], v[172:175], v[96:111]
	v_mfma_f32_32x32x16_bf16 v[32:47], v[156:159], v[248:251], v[32:47]
	s_waitcnt vmcnt(4)
	s_barrier
	ds_read_b128 v[128:131], v202 offset:49152
	ds_read_b128 v[144:147], v202 offset:53248
	ds_read_b128 v[132:135], v203 offset:49152
	ds_read_b128 v[148:151], v203 offset:53248
	ds_read_b128 v[136:139], v204 offset:49152
	ds_read_b128 v[152:155], v204 offset:53248
	ds_read_b128 v[140:143], v205 offset:49152
	ds_read_b128 v[156:159], v205 offset:53248
	s_add_u32 s6, s6, 0x80
	s_addc_u32 s7, s7, 0
	s_add_u32 m0, s13, 32768
	s_nop 0
	global_load_lds_dwordx4 v210, s[6:7]
	global_load_lds_dwordx4 v211, s[6:7] offset:1024
	global_load_lds_dwordx4 v212, s[6:7] offset:2048
	global_load_lds_dwordx4 v213, s[6:7] offset:3072
	s_waitcnt lgkmcnt(6)
	v_mfma_f32_32x32x16_bf16 v[80:95], v[128:131], v[160:163], v[80:95]
	v_mfma_f32_32x32x16_bf16 v[16:31], v[128:131], v[236:239], v[16:31]
	v_mfma_f32_32x32x16_bf16 v[64:79], v[144:147], v[160:163], v[64:79]
	v_mfma_f32_32x32x16_bf16 v[0:15], v[144:147], v[236:239], v[0:15]
	s_waitcnt lgkmcnt(4)
	v_mfma_f32_32x32x16_bf16 v[80:95], v[132:135], v[164:167], v[80:95]
	v_mfma_f32_32x32x16_bf16 v[16:31], v[132:135], v[240:243], v[16:31]
	v_mfma_f32_32x32x16_bf16 v[64:79], v[148:151], v[164:167], v[64:79]
	v_mfma_f32_32x32x16_bf16 v[0:15], v[148:151], v[240:243], v[0:15]
	s_waitcnt lgkmcnt(2)
	v_mfma_f32_32x32x16_bf16 v[80:95], v[136:139], v[168:171], v[80:95]
	v_mfma_f32_32x32x16_bf16 v[16:31], v[136:139], v[244:247], v[16:31]
	v_mfma_f32_32x32x16_bf16 v[64:79], v[152:155], v[168:171], v[64:79]
	v_mfma_f32_32x32x16_bf16 v[0:15], v[152:155], v[244:247], v[0:15]
	s_waitcnt lgkmcnt(0)
	v_mfma_f32_32x32x16_bf16 v[80:95], v[140:143], v[172:175], v[80:95]
	v_mfma_f32_32x32x16_bf16 v[16:31], v[140:143], v[248:251], v[16:31]
	v_mfma_f32_32x32x16_bf16 v[64:79], v[156:159], v[172:175], v[64:79]
	v_mfma_f32_32x32x16_bf16 v[0:15], v[156:159], v[248:251], v[0:15]
	s_waitcnt vmcnt(0)
	s_barrier
	ds_read_b128 v[160:163], v206 offset:16384
	ds_read_b128 v[236:239], v206 offset:20480
	ds_read_b128 v[128:131], v202 offset:32768
	ds_read_b128 v[144:147], v202 offset:36864
	ds_read_b128 v[164:167], v207 offset:16384
	ds_read_b128 v[240:243], v207 offset:20480
	ds_read_b128 v[132:135], v203 offset:32768
	ds_read_b128 v[148:151], v203 offset:36864
	s_add_u32 s8, s8, 0x80
	s_addc_u32 s9, s9, 0
	s_add_u32 m0, s13, 49152
	s_nop 0
	global_load_lds_dwordx4 v210, s[8:9]
	global_load_lds_dwordx4 v211, s[8:9] offset:1024
	global_load_lds_dwordx4 v212, s[8:9] offset:2048
	global_load_lds_dwordx4 v213, s[8:9] offset:3072
	s_cmp_eq_u32 s12, 7
	s_cbranch_scc1 .Lga_skipx
	s_add_u32 s10, s10, 0x80
	s_addc_u32 s11, s11, 0
	s_add_u32 m0, s13, 0
	s_nop 0
	global_load_lds_dwordx4 v216, s[10:11] sc1
	global_load_lds_dwordx4 v217, s[10:11] offset:1024 sc1
	global_load_lds_dwordx4 v218, s[10:11] offset:2048 sc1
	global_load_lds_dwordx4 v219, s[10:11] offset:3072 sc1

; DI char* opq(char* q) { size_t z = 0; asm volatile("" : "+s"(z)); return q + z; }
; DI int tidx() { int t = threadIdx.x; asm volatile("" : "+v"(t)); return t; }
; template <int NTW>
; DI void inproj_tile(const Params& p, int l, int mt, int ntile, char* lds) {
;   char* const ws_ = opq(p.ws);
;   const u16* W = (const u16*)(ws_ + OFF_WIN) + ((size_t)l * NP + ntile * 64 * NTW) * 1024;
;   const u16* X = (const u16*)(ws_ + OFF_XB) + (size_t)mt * 128 * 1024;
;   f32x16 acc[NTW][2];
;   const int tid = tidx();
;   gemm_core<2, NTW, 2, (NTW == 2)>(acc, 16, [&](int i, int r0, int k) -> u32x4 { return *(const u32x4*)((W + i * 32768) + (unsigned)(r0 * 1024 + k)); },
;                [&](int i, int r0, int k) -> u32x4 { return *(const u32x4*)((X + i * 32768) + (unsigned)(r0 * 1024 + k)); }, lds, tid);
; __global__ void __launch_bounds__(256, 2) hybrid_megakernel(Params p) {
;     ...
;       { const int q2 = vb >> 3; inproj_tile<4>(p, l, (vb & 7) * 16 + (q2 & 15), 8 + (q2 >> 4), lds); }
.Lb_tile:
	s_lshl_b32 s0, s36, 4
	s_and_b32 s0, s0, 0x70
	s_bfe_u32 s1, s36, 0x40003
	s_or_b32 s4, s0, s1
	s_mov_b64 s[0:1], 0
	s_add_u32 s27, s90, s0
	s_addc_u32 s37, s91, s1
	s_lshl_b32 s0, s36, 1
	s_and_b32 s0, s0, 0xffffff00
	s_addk_i32 s0, 0x800
	s_ashr_i32 s1, s0, 31
	s_add_u32 s2, s0, s28
	s_addc_u32 s3, s1, 0
	s_lshl_b64 s[2:3], s[2:3], 11
	s_add_u32 s2, s27, s2
	s_addc_u32 s3, s37, s3
	s_lshl_b32 s80, s4, 7
	s_lshl_b32 s26, s4, 18
	s_add_u32 s24, s27, s26
	s_addc_u32 s25, s37, 0
	s_add_u32 s4, s24, 0x2a40000
	s_addc_u32 s5, s25, 0
	v_mov_b32_e32 v181, v176
	v_and_b32_e32 v183, 0x5f, v181
	v_lshrrev_b32_e32 v185, 3, v181
	v_or_b32_e32 v254, s80, v183
	v_lshlrev_b32_e32 v254, 2, v254
	s_add_u32 s14, s27, 0x4a40000
	s_addc_u32 s15, s37, 0
	global_load_dword v252, v254, s[14:15] sc1
	global_load_dword v253, v254, s[14:15] offset:128 sc1
	v_and_b32_e32 v220, 63, v181
	v_lshrrev_b32_e32 v221, 6, v181
	v_lshrrev_b32_e32 v222, 3, v220
	v_readfirstlane_b32 s13, v221
	v_and_b32_e32 v223, 7, v220
	v_bfe_u32 v224, v220, 4, 2
	v_xor_b32_e32 v223, v223, v224
	v_lshlrev_b32_e32 v223, 4, v223
	v_and_b32_e32 v224, 1, v221
	v_lshrrev_b32_e32 v225, 1, v221
	v_lshlrev_b32_e32 v224, 5, v224
	v_lshl_add_u32 v224, v225, 7, v224
	v_add_u32_e32 v224, v224, v222
	v_lshl_add_u32 v225, v221, 5, v222
	v_lshl_or_b32 v210, v224, 11, v223
	v_lshl_or_b32 v216, v225, 11, v223
	v_xor_b32_e32 v224, 64, v210
	v_xor_b32_e32 v225, 64, v216
	v_add_u32_e32 v211, 0x3c00, v224
	v_add_u32_e32 v217, 0x3c00, v225
	v_add_u32_e32 v212, 0x7800, v210
	v_add_u32_e32 v218, 0x7800, v216
	v_add_u32_e32 v213, 0xb400, v224
	v_add_u32_e32 v219, 0xb400, v225
	v_and_b32_e32 v222, 31, v220
	v_lshrrev_b32_e32 v223, 5, v220
	v_bfe_u32 v224, v220, 1, 3
	v_xor_b32_e32 v223, v223, v224
	v_lshlrev_b32_e32 v223, 4, v223
	v_lshrrev_b32_e32 v224, 1, v221
	v_and_b32_e32 v225, 1, v221
	v_lshl_add_u32 v224, v224, 6, v222
	v_lshl_add_u32 v225, v225, 6, v222
	v_lshl_or_b32 v202, v224, 7, v223
	v_lshl_or_b32 v206, v225, 7, v223
	v_xor_b32_e32 v203, 32, v202
	v_xor_b32_e32 v207, 32, v206
	v_xor_b32_e32 v204, 64, v202
	v_xor_b32_e32 v208, 64, v206
	v_xor_b32_e32 v205, 96, v202
	v_xor_b32_e32 v209, 96, v206
	s_lshl_b32 s13, s13, 12
	s_sub_u32 s10, s4, 0x80
	s_subb_u32 s11, s5, 0
	s_add_u32 s8, s2, 0x1ff80
	s_addc_u32 s9, s3, 0
	s_sub_u32 s6, s2, 0x80
	s_subb_u32 s7, s3, 0
	s_mov_b32 s12, 0
	v_mov_b32_e32 v112, 0
	v_mov_b32_e32 v113, 0
	v_mov_b32_e32 v114, 0
	v_mov_b32_e32 v115, 0
	v_mov_b32_e32 v116, 0
	v_mov_b32_e32 v117, 0
	v_mov_b32_e32 v118, 0
	v_mov_b32_e32 v119, 0
	v_mov_b32_e32 v120, 0
	v_mov_b32_e32 v121, 0
	v_mov_b32_e32 v122, 0
	v_mov_b32_e32 v123, 0
	v_mov_b32_e32 v124, 0
	v_mov_b32_e32 v125, 0
	v_mov_b32_e32 v126, 0
	v_mov_b32_e32 v127, 0
	v_mov_b32_e32 v48, 0
	v_mov_b32_e32 v49, 0
	v_mov_b32_e32 v50, 0
	v_mov_b32_e32 v51, 0
	v_mov_b32_e32 v52, 0
	v_mov_b32_e32 v53, 0
	v_mov_b32_e32 v54, 0
	v_mov_b32_e32 v55, 0
	v_mov_b32_e32 v56, 0
	v_mov_b32_e32 v57, 0
	v_mov_b32_e32 v58, 0
	v_mov_b32_e32 v59, 0
	v_mov_b32_e32 v60, 0
	v_mov_b32_e32 v61, 0
	v_mov_b32_e32 v62, 0
	v_mov_b32_e32 v63, 0
	v_mov_b32_e32 v96, 0
	v_mov_b32_e32 v97, 0
	v_mov_b32_e32 v98, 0
	v_mov_b32_e32 v99, 0
	v_mov_b32_e32 v100, 0
	v_mov_b32_e32 v101, 0
	v_mov_b32_e32 v102, 0
	v_mov_b32_e32 v103, 0
	v_mov_b32_e32 v104, 0
	v_mov_b32_e32 v105, 0
	v_mov_b32_e32 v106, 0
	v_mov_b32_e32 v107, 0
	v_mov_b32_e32 v108, 0
	v_mov_b32_e32 v109, 0
	v_mov_b32_e32 v110, 0
	v_mov_b32_e32 v111, 0
	v_mov_b32_e32 v32, 0
	v_mov_b32_e32 v33, 0
	v_mov_b32_e32 v34, 0
	v_mov_b32_e32 v35, 0
	v_mov_b32_e32 v36, 0
	v_mov_b32_e32 v37, 0
	v_mov_b32_e32 v38, 0
	v_mov_b32_e32 v39, 0
	v_mov_b32_e32 v40, 0
	v_mov_b32_e32 v41, 0
	v_mov_b32_e32 v42, 0
	v_mov_b32_e32 v43, 0
	v_mov_b32_e32 v44, 0
	v_mov_b32_e32 v45, 0
	v_mov_b32_e32 v46, 0
	v_mov_b32_e32 v47, 0
	v_mov_b32_e32 v80, 0
	v_mov_b32_e32 v81, 0
	v_mov_b32_e32 v82, 0
	v_mov_b32_e32 v83, 0
	v_mov_b32_e32 v84, 0
	v_mov_b32_e32 v85, 0
	v_mov_b32_e32 v86, 0
	v_mov_b32_e32 v87, 0
	v_mov_b32_e32 v88, 0
	v_mov_b32_e32 v89, 0
	v_mov_b32_e32 v90, 0
	v_mov_b32_e32 v91, 0
	v_mov_b32_e32 v92, 0
	v_mov_b32_e32 v93, 0
	v_mov_b32_e32 v94, 0
	v_mov_b32_e32 v95, 0
	v_mov_b32_e32 v16, 0
	v_mov_b32_e32 v17, 0
	v_mov_b32_e32 v18, 0
	v_mov_b32_e32 v19, 0
	v_mov_b32_e32 v20, 0
	v_mov_b32_e32 v21, 0
	v_mov_b32_e32 v22, 0
	v_mov_b32_e32 v23, 0
	v_mov_b32_e32 v24, 0
	v_mov_b32_e32 v25, 0
	v_mov_b32_e32 v26, 0
	v_mov_b32_e32 v27, 0
	v_mov_b32_e32 v28, 0
	v_mov_b32_e32 v29, 0
	v_mov_b32_e32 v30, 0
	v_mov_b32_e32 v31, 0
	v_mov_b32_e32 v64, 0
	v_mov_b32_e32 v65, 0
	v_mov_b32_e32 v66, 0
	v_mov_b32_e32 v67, 0
	v_mov_b32_e32 v68, 0
	v_mov_b32_e32 v69, 0
	v_mov_b32_e32 v70, 0
	v_mov_b32_e32 v71, 0
	v_mov_b32_e32 v72, 0
	v_mov_b32_e32 v73, 0
	v_mov_b32_e32 v74, 0
	v_mov_b32_e32 v75, 0
	v_mov_b32_e32 v76, 0
	v_mov_b32_e32 v77, 0
	v_mov_b32_e32 v78, 0
	v_mov_b32_e32 v79, 0
	v_mov_b32_e32 v0, 0
	v_mov_b32_e32 v1, 0
	v_mov_b32_e32 v2, 0
	v_mov_b32_e32 v3, 0
	v_mov_b32_e32 v4, 0
	v_mov_b32_e32 v5, 0
	v_mov_b32_e32 v6, 0
	v_mov_b32_e32 v7, 0
	v_mov_b32_e32 v8, 0
	v_mov_b32_e32 v9, 0
	v_mov_b32_e32 v10, 0
	v_mov_b32_e32 v11, 0
	v_mov_b32_e32 v12, 0
	v_mov_b32_e32 v13, 0
	v_mov_b32_e32 v14, 0
	v_mov_b32_e32 v15, 0
	s_setprio 2
	s_waitcnt lgkmcnt(0)
	s_barrier
	s_add_u32 s10, s10, 0x80
	s_addc_u32 s11, s11, 0
	s_add_u32 m0, s13, 0
	s_nop 0
	global_load_lds_dwordx4 v216, s[10:11] sc1
	global_load_lds_dwordx4 v217, s[10:11] offset:1024 sc1
	global_load_lds_dwordx4 v218, s[10:11] offset:2048 sc1
	global_load_lds_dwordx4 v219, s[10:11] offset:3072 sc1
	s_add_u32 s6, s6, 0x80
	s_addc_u32 s7, s7, 0
	s_add_u32 m0, s13, 32768
	s_nop 0
	global_load_lds_dwordx4 v210, s[6:7]
	global_load_lds_dwordx4 v211, s[6:7] offset:1024
	global_load_lds_dwordx4 v212, s[6:7] offset:2048
	global_load_lds_dwordx4 v213, s[6:7] offset:3072

; DI unsigned xb_ld(unsigned* p)              { return __hip_atomic_load(p, __ATOMIC_RELAXED, __HIP_MEMORY_SCOPE_AGENT); }
; DI unsigned xb_add(unsigned* p, unsigned v) { return __hip_atomic_fetch_add(p, v, __ATOMIC_RELAXED, __HIP_MEMORY_SCOPE_AGENT); }
; #define XB_SPIN(cond, bar) do { unsigned _sp = 0; while (cond) { __builtin_amdgcn_s_sleep(1); \
;     if ((++_sp & 255u) == 0u) { if (xb_ld(&(bar)[XB_TMO])) break; if (_sp > XB_SPIN_CAP) { atomicAdd(&(bar)[XB_TMO], 1u); break; } } } } while (0)
; DI void xcd_barrier(const XcdBarrier& b) {
;     ...
;             __builtin_amdgcn_fence(__ATOMIC_ACQUIRE, "agent");
;             xb_add(&bar[XB_XGEN(b.x)], 1u);
;             asm volatile("s_waitcnt vmcnt(0)" ::: "memory");
;         } else {
;             XB_SPIN(xb_ld(&bar[XB_XGEN(b.x)]) == gen, bar);
;             __builtin_amdgcn_fence(__ATOMIC_ACQUIRE, "agent");
;             asm volatile("s_waitcnt vmcnt(0)" ::: "memory");
;         }
;     }
;     __syncthreads();
; __global__ void __launch_bounds__(256, 2) hybrid_megakernel(Params p) {
;     ...
;     xcd_barrier(xg);
;     for (int it = bid; it < 512; it += nb) outproj_item(p, l, it, lds);
;     xcd_barrier(xg);
.LBB0_542:
	s_waitcnt vmcnt(0)
	s_barrier
	s_mov_b64 s[0:1], exec
	v_readlane_b32 s2, v235, 18
	v_readlane_b32 s3, v235, 19
	s_and_b64 s[2:3], s[0:1], s[2:3]
	s_mov_b64 exec, s[2:3]
	s_cbranch_execnz .Lxg_t0_4
	s_mov_b64 exec, s[0:1]
	v_cmp_eq_u32_e64 s[2:3], 64, v176
	s_cmp_eq_u64 s[2:3], 0
	s_cbranch_scc1 .LBB0_587
	v_readlane_b32 s2, v235, 22
	s_nop 1
	v_mov_b32_e32 v0, s2
	ds_read_b32 v0, v0 offset:4
	s_waitcnt lgkmcnt(0)
	v_readfirstlane_b32 s2, v0
	s_cmp_eq_u32 s2, 1
	s_cbranch_scc1 .LBB0_587
	buffer_inv sc1
	s_waitcnt vmcnt(0)
	s_branch .LBB0_587

; DI char* opq(char* q) { size_t z = 0; asm volatile("" : "+s"(z)); return q + z; }
; DI int tidx() { int t = threadIdx.x; asm volatile("" : "+v"(t)); return t; }
; DI float lo16(unsigned w) { return __uint_as_float(w << 16); }
; DI float hi16(unsigned w) { return __uint_as_float(w & 0xffff0000u); }
; template <int NR>
; DI void resid_rows(const Params& p, int l, int row0, const float* xin) {
;   char* const ws_ = opq(p.ws);
;   const int lane = tidx() & 63;
;   const u16* outb = (const u16*)(ws_ + OFF_OUTB);
;   const float* ssq = (const float*)(ws_ + OFF_SSQ);
;   u32x2 ob[NR][4]; f32x4 xv[NR][4]; f32x4 sq[NR][2];
; #pragma unroll
;   for (int r = 0; r < NR; ++r) {
;     const size_t row = (size_t)(row0 + r);
;     sq[r][0] = *(const f32x4*)(ssq + row * 16); sq[r][1] = *(const f32x4*)(ssq + row * 16 + 4);
; #pragma unroll
;     for (int i = 0; i < 4; ++i) { const int idx = i * 256 + lane * 4; ob[r][i] = *(const u32x2*)(outb + row * 1024 + idx); xv[r][i] = *(const f32x4*)(xin + row * 1024 + idx); }
;   }
;   f32x4 gq[4];
; #pragma unroll
;   for (int i = 0; i < 4; ++i) gq[i] = *(const f32x4*)(p.g_post + l * 1024 + i * 256 + lane * 4);
;   u16* xb = (u16*)(ws_ + OFF_XB);
; #pragma unroll
;   for (int r = 0; r < NR; ++r) {
;     const size_t row = (size_t)(row0 + r);
;     const float ss = ((sq[r][0][0] + sq[r][0][1]) + (sq[r][0][2] + sq[r][0][3])) + ((sq[r][1][0] + sq[r][1][1]) + (sq[r][1][2] + sq[r][1][3]));
;     const float r2 = rsqrtf(ss * (1.f / 1024.f) + 1e-6f);
;     float s2 = 0.f;
; #pragma unroll
;     for (int i = 0; i < 4; ++i) {
;       const int idx = i * 256 + lane * 4;
;       const f32x4 o = {lo16(ob[r][i][0]), hi16(ob[r][i][0]), lo16(ob[r][i][1]), hi16(ob[r][i][1])};
;       f32x4 xn;
; #pragma unroll
;       for (int e = 0; e < 4; ++e) { xn[e] = xv[r][i][e] + o[e] * r2 * gq[i][e]; s2 += xn[e] * xn[e]; }
;       *(f32x4*)(p.out + row * 1024 + idx) = xn;
;       if (l < 3) { u32x2 o2; o2[0] = pk2(xn[0], xn[1]); o2[1] = pk2(xn[2], xn[3]); *(u32x2*)(xb + row * 1024 + idx) = o2; }
;     }
;     s2 = wave_sum(s2);
;     if (lane == 0) ((float*)(ws_ + OFF_RN))[row] = rsqrtf(s2 * (1.f / 1024.f) + 1e-6f);
;   }
.LBB0_592:
	s_mov_b64 s[6:7], 0
	s_add_u32 s8, s90, s6
	s_addc_u32 s9, s91, s7
	s_add_u32 s6, s8, 0xd4f0000
	v_mov_b32_e32 v0, v176
	s_addc_u32 s7, s9, 0
	s_add_u32 s10, s8, 0xb250000
	v_ashrrev_i32_e32 v105, 31, v104
	v_and_b32_e32 v149, 63, v0
	s_addc_u32 s11, s9, 0
	s_waitcnt lgkmcnt(0)
	v_lshlrev_b64 v[0:1], 6, v[104:105]
	v_lshl_add_u64 v[0:1], s[10:11], 0, v[0:1]
	v_lshlrev_b64 v[146:147], 11, v[104:105]
	v_lshlrev_b64 v[154:155], 12, v[104:105]
	global_load_dwordx4 v[100:103], v[0:1], off sc1
	global_load_dwordx4 v[142:145], v[0:1], off offset:16 sc1
	v_lshl_add_u64 v[0:1], s[6:7], 0, v[146:147]
	v_lshl_add_u64 v[2:3], s[0:1], 0, v[154:155]
	v_lshlrev_b32_e32 v178, 3, v149
	v_lshlrev_b32_e32 v156, 4, v149
	v_mov_b32_e32 v157, v179
	v_add_u32_e32 v124, 1, v104
	v_lshl_add_u64 v[0:1], v[0:1], 0, v[178:179]
	v_lshl_add_u64 v[2:3], v[2:3], 0, v[156:157]
	v_ashrrev_i32_e32 v125, 31, v124
	global_load_dwordx4 v[150:153], v[2:3], off nt
	global_load_dwordx4 v[96:99], v[2:3], off offset:1024 nt
	global_load_dwordx2 v[158:159], v[0:1], off sc1
	global_load_dwordx2 v[140:141], v[0:1], off offset:512 sc1
	global_load_dwordx2 v[138:139], v[0:1], off offset:1024 sc1
	global_load_dwordx2 v[136:137], v[0:1], off offset:1536 sc1
	global_load_dwordx4 v[92:95], v[2:3], off offset:2048 nt
	global_load_dwordx4 v[88:91], v[2:3], off offset:3072 nt
	v_lshlrev_b64 v[0:1], 6, v[124:125]
	v_lshl_add_u64 v[0:1], s[10:11], 0, v[0:1]
	global_load_dwordx4 v[80:83], v[0:1], off offset:16 sc1
	global_load_dwordx4 v[84:87], v[0:1], off sc1
	v_lshlrev_b64 v[0:1], 11, v[124:125]
	v_lshlrev_b64 v[2:3], 12, v[124:125]
	v_lshl_add_u64 v[0:1], s[6:7], 0, v[0:1]
	v_lshl_add_u64 v[2:3], s[0:1], 0, v[2:3]
	v_add_u32_e32 v114, 2, v104
	v_lshl_add_u64 v[0:1], v[0:1], 0, v[178:179]
	v_lshl_add_u64 v[2:3], v[2:3], 0, v[156:157]
	v_ashrrev_i32_e32 v115, 31, v114
	global_load_dwordx4 v[76:79], v[2:3], off nt
	global_load_dwordx4 v[72:75], v[2:3], off offset:1024 nt
	global_load_dwordx2 v[134:135], v[0:1], off sc1
	global_load_dwordx2 v[132:133], v[0:1], off offset:512 sc1
	global_load_dwordx2 v[130:131], v[0:1], off offset:1024 sc1
	global_load_dwordx2 v[128:129], v[0:1], off offset:1536 sc1
	global_load_dwordx4 v[68:71], v[2:3], off offset:2048 nt
	global_load_dwordx4 v[64:67], v[2:3], off offset:3072 nt
	v_lshlrev_b64 v[0:1], 6, v[114:115]
	v_lshl_add_u64 v[0:1], s[10:11], 0, v[0:1]
	v_lshlrev_b64 v[2:3], 12, v[114:115]
	global_load_dwordx4 v[56:59], v[0:1], off offset:16 sc1
	global_load_dwordx4 v[60:63], v[0:1], off sc1
	v_lshlrev_b64 v[0:1], 11, v[114:115]
	v_lshl_add_u64 v[2:3], s[0:1], 0, v[2:3]
	v_lshl_add_u64 v[0:1], s[6:7], 0, v[0:1]
	v_lshl_add_u64 v[2:3], v[2:3], 0, v[156:157]
	v_lshl_add_u64 v[0:1], v[0:1], 0, v[178:179]
	global_load_dwordx4 v[52:55], v[2:3], off nt
	global_load_dwordx4 v[48:51], v[2:3], off offset:1024 nt
	global_load_dwordx2 v[126:127], v[0:1], off sc1
	global_load_dwordx2 v[122:123], v[0:1], off offset:512 sc1
	global_load_dwordx2 v[120:121], v[0:1], off offset:1024 sc1
	global_load_dwordx2 v[118:119], v[0:1], off offset:1536 sc1
	global_load_dwordx4 v[44:47], v[2:3], off offset:2048 nt
	global_load_dwordx4 v[40:43], v[2:3], off offset:3072 nt
	v_add_u32_e32 v106, 3, v104
	v_ashrrev_i32_e32 v107, 31, v106
	v_lshlrev_b64 v[0:1], 6, v[106:107]
	v_lshl_add_u64 v[0:1], s[10:11], 0, v[0:1]
	global_load_dwordx4 v[32:35], v[0:1], off offset:16 sc1
	global_load_dwordx4 v[36:39], v[0:1], off sc1
	v_lshlrev_b64 v[0:1], 11, v[106:107]
	v_lshlrev_b64 v[2:3], 12, v[106:107]
	v_lshl_add_u64 v[0:1], s[6:7], 0, v[0:1]
	v_lshl_add_u64 v[2:3], s[0:1], 0, v[2:3]
	v_lshl_add_u64 v[0:1], v[0:1], 0, v[178:179]
	v_lshl_add_u64 v[2:3], v[2:3], 0, v[156:157]
	global_load_dwordx4 v[24:27], v156, s[2:3]
	global_load_dwordx4 v[28:31], v[2:3], off nt
	global_load_dwordx4 v[16:19], v[2:3], off offset:1024 nt
	global_load_dwordx2 v[116:117], v[0:1], off sc1
	global_load_dwordx2 v[112:113], v[0:1], off offset:512 sc1
	global_load_dwordx2 v[110:111], v[0:1], off offset:1024 sc1
	global_load_dwordx2 v[108:109], v[0:1], off offset:1536 sc1
	global_load_dwordx4 v[8:11], v[2:3], off offset:2048 nt
	s_nop 0
	global_load_dwordx4 v[0:3], v[2:3], off offset:3072 nt
	s_nop 0
	global_load_dwordx4 v[20:23], v156, s[2:3] offset:1024
	global_load_dwordx4 v[12:15], v156, s[2:3] offset:2048
	global_load_dwordx4 v[4:7], v156, s[2:3] offset:3072
	s_add_u32 s6, s8, 0x2a40000
	s_addc_u32 s7, s9, 0
	v_lshlrev_b32_e32 v148, 2, v149
	s_waitcnt vmcnt(43)
	v_mov_b32_e32 v160, v100
	s_waitcnt vmcnt(42)
	v_mov_b32_e32 v161, v142
	v_mov_b32_e32 v142, v101
	v_pk_add_f32 v[100:101], v[160:161], v[142:143]
	v_mov_b32_e32 v142, v102
	v_mov_b32_e32 v143, v144
	v_mov_b32_e32 v144, v103
	v_pk_add_f32 v[102:103], v[142:143], v[144:145]
	v_lshl_add_u64 v[142:143], s[6:7], 0, v[146:147]
	v_pk_add_f32 v[100:101], v[100:101], v[102:103]
	s_waitcnt vmcnt(39)
	v_lshlrev_b32_e32 v102, 16, v159
	v_add_f32_e32 v100, v100, v101
	v_fmamk_f32 v100, v100, 0x3a800000, v192
	v_mul_f32_e32 v101, 0x4b800000, v100
	v_cmp_gt_f32_e32 vcc, s92, v100
	v_and_b32_e32 v103, 0xffff0000, v159
	v_lshl_add_u64 v[146:147], s[88:89], 0, v[154:155]
	v_cndmask_b32_e32 v100, v100, v101, vcc
	v_rsq_f32_e32 v100, v100
	v_lshl_add_u64 v[146:147], v[146:147], 0, v[156:157]
	v_mul_f32_e32 v101, 0x45800000, v100
	v_cndmask_b32_e32 v144, v100, v101, vcc
	v_lshlrev_b32_e32 v100, 16, v158
	v_and_b32_e32 v101, 0xffff0000, v158
	v_pk_mul_f32 v[100:101], v[144:145], v[100:101] op_sel_hi:[0,1]
	v_pk_mul_f32 v[102:103], v[144:145], v[102:103] op_sel_hi:[0,1]
	v_cndmask_b32_e64 v145, 0, 1, s[4:5]
	v_cmp_ne_u32_e64 s[36:37], 1, v145
	s_andn2_b64 vcc, exec, s[4:5]
	s_waitcnt vmcnt(11)
	v_pk_fma_f32 v[100:101], v[100:101], v[24:25], v[150:151]
	v_pk_fma_f32 v[102:103], v[102:103], v[26:27], v[152:153]
	global_store_dwordx4 v[146:147], v[100:103], off nt
	s_cbranch_vccnz .LBB0_594
	v_lshlrev_b32_e32 v178, 1, v148
	v_cvt_pk_bf16_f32 v150, v100, v101
	v_cvt_pk_bf16_f32 v151, v102, v103
	v_lshl_add_u64 v[152:153], v[142:143], 0, v[178:179]
	global_store_dwordx2 v[152:153], v[150:151], off

; DI unsigned xb_ld(unsigned* p)              { return __hip_atomic_load(p, __ATOMIC_RELAXED, __HIP_MEMORY_SCOPE_AGENT); }
; DI unsigned xb_add(unsigned* p, unsigned v) { return __hip_atomic_fetch_add(p, v, __ATOMIC_RELAXED, __HIP_MEMORY_SCOPE_AGENT); }
; #define XB_SPIN(cond, bar) do { unsigned _sp = 0; while (cond) { __builtin_amdgcn_s_sleep(1); \
;     if ((++_sp & 255u) == 0u) { if (xb_ld(&(bar)[XB_TMO])) break; if (_sp > XB_SPIN_CAP) { atomicAdd(&(bar)[XB_TMO], 1u); break; } } } } while (0)
; DI void xcd_barrier(const XcdBarrier& b) {
;     ...
;             __builtin_amdgcn_fence(__ATOMIC_ACQUIRE, "agent");
;             xb_add(&bar[XB_XGEN(b.x)], 1u);
;             asm volatile("s_waitcnt vmcnt(0)" ::: "memory");
;         } else {
;             XB_SPIN(xb_ld(&bar[XB_XGEN(b.x)]) == gen, bar);
;             __builtin_amdgcn_fence(__ATOMIC_ACQUIRE, "agent");
;             asm volatile("s_waitcnt vmcnt(0)" ::: "memory");
;         }
;     }
;     __syncthreads();
; __global__ void __launch_bounds__(256, 2) hybrid_megakernel(Params p) {
;     ...
;     if (l < 3) xcd_barrier(xg);
;   }
.LBB0_632:
	v_readlane_b32 s0, v234, 24
	s_cmp_lg_u32 s0, 3
	s_cbranch_scc0 .LBB0_160
	s_waitcnt vmcnt(0)
	s_waitcnt lgkmcnt(0)
	s_barrier
	s_mov_b64 s[0:1], exec
	v_readlane_b32 s2, v235, 18
	v_readlane_b32 s3, v235, 19
	s_and_b64 s[2:3], s[0:1], s[2:3]
	s_mov_b64 exec, s[2:3]
	s_cbranch_execnz .Lxg_t0_5
	s_mov_b64 exec, s[0:1]
	v_cmp_eq_u32_e64 s[2:3], 64, v176
	s_cmp_eq_u64 s[2:3], 0
	s_cbranch_scc1 .LBB0_159
	v_readlane_b32 s2, v235, 22
	s_nop 1
	v_mov_b32_e32 v0, s2
	ds_read_b32 v0, v0 offset:4
	s_waitcnt lgkmcnt(0)
	v_readfirstlane_b32 s2, v0
	s_cmp_eq_u32 s2, 1
	s_cbranch_scc1 .LBB0_159
	buffer_inv sc1
	s_waitcnt vmcnt(0)
	s_branch .LBB0_159
